# GQA loop trimmed: 7 redundant s_nop 0 in max chain removed, ones fragment hoisted out of loop, PV second-half waits merged (on top of v36)
# baseline (speedup 1.0000x reference)
; template <int KIND> ...
;     ...
;         const int krow_l = tid >> 3, kpart = tid & 7;
;     ...
;         float m_ref = 0.f; int first = 1;
;         f32x16 o[NDT], lacc, mneg;
; #pragma unroll
;         for (int dt = 0; dt < NDT; ++dt)
; #pragma unroll
;             for (int j = 0; j < 16; ++j) o[dt][j] = 0.f;
; #pragma unroll
;         for (int j = 0; j < 16; ++j) { lacc[j] = 0.f; mneg[j] = 0.f; }
;         const bf16x8 ones = {(short)0x3F80, (short)0x3F80, (short)0x3F80, (short)0x3F80, (short)0x3F80, (short)0x3F80, (short)0x3F80, (short)0x3F80};
;         ATT_LOAD(0); ATT_STORE(0); __syncthreads();
;         const int koff = kidx * KT + l32 * KSTR + 16 * hi;
;         const int voff = OFF_V + (4 * hi + ((lane & 15) >> 2)) * VSTR + (16 * ((lane >> 4) & 1) + 4 * (lane & 3)) * 2;
;         const int wb = 4 * hi - cs;
;         const int boff0 = OFF_BIAS + 4 * (cs - qc + 15 + wb);
.LBB0_97:
	s_and_b64 s[2:3], s[6:7], exec
	s_movk_i32 s2, 0x880
	s_cselect_b32 s2, s2, 0x800
	s_cmp_ge_i32 s74, s2
	s_cbranch_scc1 .LBB0_171
	v_ashrrev_i32_e32 v3, 31, v198
	v_lshrrev_b32_e32 v3, 29, v3
	v_add_u32_e32 v3, v198, v3
	s_waitcnt vmcnt(0)
	v_ashrrev_i32_e32 v151, 3, v198
	v_and_b32_e32 v2, 7, v196
	v_ashrrev_i32_e32 v152, 3, v3
	v_and_b32_e32 v3, -8, v3
	v_sub_u32_e32 v3, v198, v3
	v_mul_lo_u32 v4, v151, s90
	v_lshlrev_b32_e32 v192, 4, v2
	s_movk_i32 s4, 0xc0
	v_ashrrev_i32_e32 v1, 5, v196
	v_lshlrev_b32_e32 v0, 3, v2
	v_lshlrev_b32_e32 v138, 3, v3
	v_add3_u32 v153, 0, v4, v192
	v_mul_lo_u32 v2, v152, s4
	v_lshlrev_b32_e32 v3, 4, v3
	v_bfe_u32 v4, v196, 2, 2
	v_lshlrev_b32_e32 v136, 3, v1
	v_add3_u32 v154, 0, v2, v3
	v_lshlrev_b32_e32 v3, 4, v1
	v_lshl_or_b32 v1, v1, 2, v4
	v_and_b32_e32 v4, 16, v196
	v_lshlrev_b32_e32 v5, 2, v196
	v_and_or_b32 v4, v5, 12, v4
	v_and_b32_e32 v150, 31, v196
	v_mul_lo_u32 v1, v1, s4
	v_lshlrev_b32_e32 v4, 1, v4
	v_cmp_lt_i32_e32 vcc, v223, v217
	v_ashrrev_i32_e32 v139, 31, v138
	v_mul_u32_u24_e32 v2, 0x90, v150
	v_add3_u32 v156, 0, v1, v4
	s_mul_i32 s4, s38, 0x1200
	v_cndmask_b32_e32 v1, v216, v223, vcc
	s_lshl_b32 s3, s38, 5
	v_ashrrev_i32_e32 v137, 31, v136
	v_add3_u32 v155, 0, v2, v3
	v_lshl_add_u64 v[140:141], s[58:59], 0, v[192:193]
	v_lshl_add_u64 v[142:143], v[138:139], 1, s[58:59]
	s_add_i32 s14, s4, 0
	v_lshlrev_b32_e32 v157, 2, v1
	v_add_u32_e32 v158, 0x80, v152
	v_add_u32_e32 v159, 0x80, v151
	v_lshlrev_b32_e32 v144, 1, v0
	v_mov_b64_e32 v[186:187], s[84:85]
	v_mov_b64_e32 v[188:189], s[86:87]
	s_mov_b32 s15, s74
	s_branch .LBB0_100

; template <int KIND> ...
;     ...
;                 {
;                     constexpr int NM = 2 * (1 + NDT);
;                     int mi = 0;
; #pragma unroll
;                     for (int s = 0; s < 2; ++s) {
;                         lacc = __builtin_amdgcn_mfma_f32_32x32x16_bf16(ones, pf[s], lacc, 0, 0, 0);
; #pragma unroll
;                         for (int j = (mi * 16) / NM; j < ((mi + 1) * 16) / NM; ++j) s1[j] = __builtin_amdgcn_exp2f(s1[j]);
;                         ++mi;
; #pragma unroll
;                         for (int dt = 0; dt < NDT; ++dt) {
;                             const s16x4 va = vfa[s][dt][0], vb = vfa[s][dt][1];
;                             const bf16x8 vf = {va[0], va[1], va[2], va[3], vb[0], vb[1], vb[2], vb[3]};
;                             o[dt] = __builtin_amdgcn_mfma_f32_32x32x16_bf16(vf, pf[s], o[dt], 0, 0, 0);
; #pragma unroll
;                             for (int j = (mi * 16) / NM; j < ((mi + 1) * 16) / NM; ++j) s1[j] = __builtin_amdgcn_exp2f(s1[j]);
;                             ++mi;
;                         }
;                     }
; #pragma unroll
;                     for (int q = 0; q < 2; ++q) { u32x4 w; w.x = pk2n(s1[8 * q + 0], s1[8 * q + 1]); w.y = pk2n(s1[8 * q + 2], s1[8 * q + 3]); w.z = pk2n(s1[8 * q + 4], s1[8 * q + 5]); w.w = pk2n(s1[8 * q + 6], s1[8 * q + 7]);
;                         pf[q + 2] = __builtin_bit_cast(bf16x8, w); }
; #pragma unroll
;                     for (int i = 0; i < NM; ++i) { __builtin_amdgcn_sched_group_barrier(0x008, 1, 0); __builtin_amdgcn_sched_group_barrier(0x402, (16 + NM - 1) / NM + 1, 0); }
;                 }
;                 __builtin_amdgcn_sched_barrier(0);
; #pragma unroll
;                 for (int s = 0; s < 2; ++s) {
;                     lacc = __builtin_amdgcn_mfma_f32_32x32x16_bf16(ones, pf[s + 2], lacc, 0, 0, 0);
; #pragma unroll
;                     for (int dt = 0; dt < NDT; ++dt) {
;                         const s16x4 va = vfb[s][dt][0], vb = vfb[s][dt][1];
;                         const bf16x8 vf = {va[0], va[1], va[2], va[3], vb[0], vb[1], vb[2], vb[3]};
;                         o[dt] = __builtin_amdgcn_mfma_f32_32x32x16_bf16(vf, pf[s + 2], o[dt], 0, 0, 0);
;                     }
;                 }
;                 __builtin_amdgcn_sched_barrier(0);
;             }
;             if (t + 1 < nt) ATT_STORE((t + 1) & 1);
;             __syncthreads();
.LBB0_109:
	s_nop 0
	v_exp_f32_e32 v80, v80
	v_exp_f32_e32 v81, v81
	v_exp_f32_e32 v82, v82
	v_exp_f32_e32 v83, v83
	v_exp_f32_e32 v84, v84
	v_exp_f32_e32 v85, v85
	v_exp_f32_e32 v86, v86
	v_exp_f32_e32 v87, v87
	v_exp_f32_e32 v88, v88
	v_exp_f32_e32 v89, v89
	v_exp_f32_e32 v90, v90
	v_exp_f32_e32 v91, v91
	v_exp_f32_e32 v92, v92
	v_exp_f32_e32 v93, v93
	v_exp_f32_e32 v94, v94
	v_exp_f32_e32 v95, v95
	v_cvt_pk_bf16_f32 v80, v80, v81
	v_cvt_pk_bf16_f32 v81, v82, v83
	v_cvt_pk_bf16_f32 v82, v84, v85
	v_cvt_pk_bf16_f32 v83, v86, v87
	v_cvt_pk_bf16_f32 v84, v88, v89
	v_cvt_pk_bf16_f32 v85, v90, v91
	v_cvt_pk_bf16_f32 v86, v92, v93
	v_cvt_pk_bf16_f32 v87, v94, v95
	s_waitcnt lgkmcnt(6)
	v_mfma_f32_32x32x16_bf16 v[16:31], v[132:135], v[80:83], v[16:31]
	v_exp_f32_e32 v92, v64
	v_exp_f32_e32 v93, v65
	ds_read_b64_tr_b16 v[64:65], v161 offset:24576
	v_mfma_f32_32x32x16_bf16 v[48:63], v[186:189], v[80:83], v[48:63]
	v_exp_f32_e32 v94, v66
	v_exp_f32_e32 v95, v67
	v_exp_f32_e32 v132, v68
	v_exp_f32_e32 v133, v69
	ds_read_b64_tr_b16 v[66:67], v161 offset:26112
	ds_read_b64_tr_b16 v[68:69], v161 offset:24640
	s_waitcnt lgkmcnt(7)
	v_mfma_f32_32x32x16_bf16 v[0:15], v[128:131], v[80:83], v[0:15]
	v_exp_f32_e32 v134, v70
	v_exp_f32_e32 v135, v71
	v_exp_f32_e32 v128, v72
	v_exp_f32_e32 v129, v73
	ds_read_b64_tr_b16 v[70:71], v161 offset:26176
	ds_read_b64_tr_b16 v[72:73], v161 offset:27648
	v_mfma_f32_32x32x16_bf16 v[48:63], v[186:189], v[84:87], v[48:63]
	v_exp_f32_e32 v130, v74
	v_exp_f32_e32 v131, v75
	v_exp_f32_e32 v162, v76
	v_exp_f32_e32 v163, v77
	ds_read_b64_tr_b16 v[74:75], v161 offset:29184
	ds_read_b64_tr_b16 v[76:77], v161 offset:27712
	s_waitcnt lgkmcnt(9)
	v_mfma_f32_32x32x16_bf16 v[16:31], v[124:127], v[84:87], v[16:31]
	v_exp_f32_e32 v164, v78
	v_exp_f32_e32 v165, v79
	v_cvt_pk_bf16_f32 v80, v92, v93
	v_cvt_pk_bf16_f32 v81, v94, v95
	ds_read_b64_tr_b16 v[78:79], v161 offset:29248
	s_waitcnt lgkmcnt(8)
	v_mfma_f32_32x32x16_bf16 v[0:15], v[120:123], v[84:87], v[0:15]
	v_cvt_pk_bf16_f32 v82, v132, v133
	v_cvt_pk_bf16_f32 v83, v134, v135
	v_cvt_pk_bf16_f32 v84, v128, v129
	v_cvt_pk_bf16_f32 v85, v130, v131
	v_cvt_pk_bf16_f32 v86, v162, v163
	v_cvt_pk_bf16_f32 v87, v164, v165
	s_waitcnt lgkmcnt(0)
	v_mfma_f32_32x32x16_bf16 v[16:31], v[64:67], v[80:83], v[16:31]
	s_and_b32 s17, s11, 1
	s_mul_i32 s19, s17, 0x2400
	s_mulk_i32 s17, 0x3000
	v_add_u32_e32 v182, s19, v153
	s_waitcnt vmcnt(1)
	ds_write_b128 v182, v[96:99]
	v_add_u32_e32 v182, s17, v154
	s_waitcnt vmcnt(0)
	ds_write_b128 v182, v[100:103] offset:18432
	v_mfma_f32_32x32x16_bf16 v[0:15], v[68:71], v[80:83], v[0:15]
	v_mfma_f32_32x32x16_bf16 v[48:63], v[186:189], v[80:83], v[48:63]
	v_mfma_f32_32x32x16_bf16 v[16:31], v[72:75], v[84:87], v[16:31]
	v_mfma_f32_32x32x16_bf16 v[0:15], v[76:79], v[84:87], v[0:15]
	v_mfma_f32_32x32x16_bf16 v[48:63], v[186:189], v[84:87], v[48:63]
	s_add_i32 s10, s10, 1
	v_add_u32_e32 v160, 64, v160
	s_cmp_eq_u32 s5, s10
	v_add_u32_e32 v145, 64, v145
	s_waitcnt lgkmcnt(0)
	s_barrier
	s_cbranch_scc1 .LBB0_112
; #define LAS __attribute__((address_space(3)))
; template <int KIND> ...
;     ...
;             if (t + 1 < nt) ATT_LOAD(t + 1);
;             bool active = true;
;             if (KIND == 0 && t < n1) { const int kr = kr_lo + t; active = (kr >= rs_w) && (kr < rs_w + 8); }
;             if (__builtin_amdgcn_readfirstlane((int)active)) {
;                 const int buf = t & 1;
;                 bf16x8 kf[8];
; #pragma unroll
;                 for (int t4 = 0; t4 < 4; ++t4) { kf[2 * t4] = *(const LAS bf16x8*)(lds + buf * KBUF + koff + 32 * t4); kf[2 * t4 + 1] = *(const LAS bf16x8*)(lds + buf * KBUF + koff + 32 * KSTR + 32 * t4); }
;                 __builtin_amdgcn_sched_barrier(0);
;                 f32x16 s0, s1;
; #pragma unroll
;                 for (int t4 = 0; t4 < 4; ++t4) {
;                     s0 = __builtin_amdgcn_mfma_f32_32x32x16_bf16(kf[2 * t4], qf[t4], t4 == 0 ? mneg : s0, 0, 0, 0);
;                     s1 = __builtin_amdgcn_mfma_f32_32x32x16_bf16(kf[2 * t4 + 1], qf[t4], t4 == 0 ? mneg : s1, 0, 0, 0);
;                 }
;                 float ab0[16], ab1[16];
;                 const bool na_lat = (KIND == 0) && (t < n1);
;                 if (na_lat) {
;                     const int bo = boff0 + (kr_lo + t - qr + 7) * 124;
; #pragma unroll
;                     for (int j = 0; j < 16; ++j) {
;                         const int C0 = 8 * (j >> 2) + (j & 3), C1 = 32 + C0;
;                         const float b0 = *(const LAS float*)(lds + bo + 4 * C0), b1 = *(const LAS float*)(lds + bo + 4 * C1);
;                         ab0[j] = ((unsigned)(wb + C0) < 16u) ? b0 : -1e30f;
;                         ab1[j] = ((unsigned)(wb + C1) < 16u) ? b1 : -1e30f;
;                     }
; #pragma unroll
;                     for (int i = 0; i < 8; ++i) { __builtin_amdgcn_sched_group_barrier(0x008, 1, 0); __builtin_amdgcn_sched_group_barrier(0x100, 4, 0); __builtin_amdgcn_sched_group_barrier(0x002, 12, 0); }
;                 }
;                 __builtin_amdgcn_sched_barrier(0);
;                 s16x4 vfa[2][NDT][2], vfb[2][NDT][2];
; #pragma unroll
;                 for (int s = 0; s < 2; ++s)
; #pragma unroll
;                     for (int dt = 0; dt < NDT; ++dt) {
;                         vfa[s][dt][0] = __builtin_amdgcn_ds_read_tr16_b64_v4i16((LAS s16x4*)(lds + buf * VBUF + voff + (16 * s) * VSTR + 64 * dt));
.LBB0_110:
	s_add_i32 s17, s10, -1
	s_add_i32 s11, s10, 4
	s_and_b32 s17, s17, 1
	s_mul_i32 s19, s17, 0x2400
	v_add_u32_e32 v68, s19, v155
	ds_read_b128 v[64:67], v68
	ds_read_b128 v[120:123], v68 offset:32
	ds_read_b128 v[124:127], v68 offset:4608
	ds_read_b128 v[128:131], v68 offset:4640
	ds_read_b128 v[132:135], v68 offset:64
	ds_read_b128 v[162:165], v68 offset:96
	ds_read_b128 v[166:169], v68 offset:4672
	ds_read_b128 v[170:173], v68 offset:4704
	s_cmp_lt_u32 s11, s5
	s_cselect_b32 s20, 0, s5
	s_cselect_b32 s21, s13, s16
	s_lshl_b32 s20, s20, 6
	s_sub_i32 s20, s21, s20
	v_add_u32_e32 v182, s20, v145
	v_mad_i64_i32 v[182:183], vcc, v182, s23, v[148:149]
	global_load_dwordx4 v[96:99], v[182:183], off offset:2048
	v_add_u32_e32 v182, s20, v160
	v_mad_i64_i32 v[182:183], vcc, v182, s23, v[146:147]
	global_load_dwordx4 v[100:103], v[182:183], off offset:2560
	s_waitcnt lgkmcnt(7)
	v_mfma_f32_32x32x16_bf16 v[80:95], v[64:67], v[116:119], v[32:47]
	s_mulk_i32 s17, 0x3000
	v_add_u32_e32 v161, s17, v156
	s_waitcnt lgkmcnt(5)
	v_mfma_f32_32x32x16_bf16 v[64:79], v[124:127], v[116:119], v[32:47]
	v_mfma_f32_32x32x16_bf16 v[80:95], v[120:123], v[112:115], v[80:95]
	s_waitcnt lgkmcnt(4)
	v_mfma_f32_32x32x16_bf16 v[64:79], v[128:131], v[112:115], v[64:79]
	s_waitcnt lgkmcnt(3)
	v_mfma_f32_32x32x16_bf16 v[80:95], v[132:135], v[108:111], v[80:95]
	ds_read_b64_tr_b16 v[132:133], v161 offset:18432
	ds_read_b64_tr_b16 v[134:135], v161 offset:19968
	ds_read_b64_tr_b16 v[130:131], v161 offset:20032
	ds_read_b64_tr_b16 v[128:129], v161 offset:18496
	ds_read_b64_tr_b16 v[124:125], v161 offset:21504
	ds_read_b64_tr_b16 v[126:127], v161 offset:23040
	ds_read_b64_tr_b16 v[122:123], v161 offset:23104
	ds_read_b64_tr_b16 v[120:121], v161 offset:21568
	s_waitcnt lgkmcnt(9)
	v_mfma_f32_32x32x16_bf16 v[64:79], v[166:169], v[108:111], v[64:79]
	v_mfma_f32_32x32x16_bf16 v[80:95], v[162:165], v[104:107], v[80:95]
	s_waitcnt lgkmcnt(8)
	v_mfma_f32_32x32x16_bf16 v[64:79], v[170:173], v[104:107], v[64:79]
	s_nop 9
	v_max_f32_e32 v162, v95, v95
	s_nop 0
	v_max_f32_e32 v163, v79, v79
	v_max_f32_e32 v162, v163, v162
	v_max3_f32 v163, v162, v80, v64
	v_max3_f32 v162, v162, v81, v65
	s_mov_b32 s17, 0x41000000
	v_max3_f32 v163, v163, v82, v66
	v_max3_f32 v162, v162, v83, v67
	v_max3_f32 v163, v163, v84, v68
	v_max3_f32 v162, v162, v85, v69
	v_max3_f32 v163, v163, v86, v70
	v_max3_f32 v162, v162, v87, v71
	v_max3_f32 v163, v163, v88, v72
	v_max3_f32 v162, v162, v89, v73
	v_max3_f32 v163, v163, v90, v74
	v_max3_f32 v162, v162, v91, v75
	v_max3_f32 v163, v163, v92, v76
	v_max3_f32 v162, v162, v93, v77
	v_max3_f32 v163, v163, v94, v78
	v_max3_f32 v162, v162, v95, v79
	v_max_f32_e32 v162, v162, v162
	v_max_f32_e32 v163, v163, v163
	v_max_f32_e32 v162, v163, v162
	v_cmp_lt_f32_e32 vcc, s17, v162
	s_cbranch_vccz .LBB0_109
	ds_bpermute_b32 v163, v157, v162
	s_waitcnt lgkmcnt(0)
	v_max3_f32 v162, v162, v163, 0
	v_exp_f32_e64 v164, -v162
	v_pk_add_f32 v[80:81], v[80:81], v[162:163] op_sel_hi:[1,0] neg_lo:[0,1] neg_hi:[0,1]
	v_pk_add_f32 v[64:65], v[64:65], v[162:163] op_sel_hi:[1,0] neg_lo:[0,1] neg_hi:[0,1]
	v_pk_add_f32 v[82:83], v[82:83], v[162:163] op_sel_hi:[1,0] neg_lo:[0,1] neg_hi:[0,1]
	v_pk_add_f32 v[66:67], v[66:67], v[162:163] op_sel_hi:[1,0] neg_lo:[0,1] neg_hi:[0,1]
	v_pk_add_f32 v[84:85], v[84:85], v[162:163] op_sel_hi:[1,0] neg_lo:[0,1] neg_hi:[0,1]
	v_pk_add_f32 v[68:69], v[68:69], v[162:163] op_sel_hi:[1,0] neg_lo:[0,1] neg_hi:[0,1]
	v_pk_add_f32 v[86:87], v[86:87], v[162:163] op_sel_hi:[1,0] neg_lo:[0,1] neg_hi:[0,1]
	v_pk_add_f32 v[70:71], v[70:71], v[162:163] op_sel_hi:[1,0] neg_lo:[0,1] neg_hi:[0,1]
	v_pk_add_f32 v[88:89], v[88:89], v[162:163] op_sel_hi:[1,0] neg_lo:[0,1] neg_hi:[0,1]
	v_pk_add_f32 v[72:73], v[72:73], v[162:163] op_sel_hi:[1,0] neg_lo:[0,1] neg_hi:[0,1]
	v_pk_add_f32 v[90:91], v[90:91], v[162:163] op_sel_hi:[1,0] neg_lo:[0,1] neg_hi:[0,1]
	v_pk_add_f32 v[74:75], v[74:75], v[162:163] op_sel_hi:[1,0] neg_lo:[0,1] neg_hi:[0,1]
	v_pk_add_f32 v[92:93], v[92:93], v[162:163] op_sel_hi:[1,0] neg_lo:[0,1] neg_hi:[0,1]
	v_pk_add_f32 v[76:77], v[76:77], v[162:163] op_sel_hi:[1,0] neg_lo:[0,1] neg_hi:[0,1]
	v_pk_add_f32 v[94:95], v[94:95], v[162:163] op_sel_hi:[1,0] neg_lo:[0,1] neg_hi:[0,1]
	v_pk_add_f32 v[78:79], v[78:79], v[162:163] op_sel_hi:[1,0] neg_lo:[0,1] neg_hi:[0,1]
	v_pk_mul_f32 v[62:63], v[62:63], v[164:165] op_sel_hi:[1,0]
	v_pk_mul_f32 v[60:61], v[60:61], v[164:165] op_sel_hi:[1,0]
	v_pk_mul_f32 v[58:59], v[58:59], v[164:165] op_sel_hi:[1,0]
	v_pk_mul_f32 v[56:57], v[56:57], v[164:165] op_sel_hi:[1,0]
	v_pk_mul_f32 v[54:55], v[54:55], v[164:165] op_sel_hi:[1,0]
	v_pk_mul_f32 v[52:53], v[52:53], v[164:165] op_sel_hi:[1,0]
	v_pk_mul_f32 v[50:51], v[50:51], v[164:165] op_sel_hi:[1,0]
	v_pk_mul_f32 v[48:49], v[48:49], v[164:165] op_sel_hi:[1,0]
	v_pk_mul_f32 v[14:15], v[14:15], v[164:165] op_sel_hi:[1,0]
	v_pk_mul_f32 v[12:13], v[12:13], v[164:165] op_sel_hi:[1,0]
	v_pk_mul_f32 v[10:11], v[10:11], v[164:165] op_sel_hi:[1,0]
	v_pk_mul_f32 v[8:9], v[8:9], v[164:165] op_sel_hi:[1,0]
	v_pk_mul_f32 v[6:7], v[6:7], v[164:165] op_sel_hi:[1,0]
	v_pk_mul_f32 v[4:5], v[4:5], v[164:165] op_sel_hi:[1,0]
	v_pk_mul_f32 v[2:3], v[2:3], v[164:165] op_sel_hi:[1,0]
	v_pk_mul_f32 v[0:1], v[0:1], v[164:165] op_sel_hi:[1,0]
	v_pk_mul_f32 v[30:31], v[30:31], v[164:165] op_sel_hi:[1,0]
	v_pk_mul_f32 v[28:29], v[28:29], v[164:165] op_sel_hi:[1,0]
	v_pk_mul_f32 v[26:27], v[26:27], v[164:165] op_sel_hi:[1,0]
	v_pk_mul_f32 v[24:25], v[24:25], v[164:165] op_sel_hi:[1,0]
	v_pk_mul_f32 v[22:23], v[22:23], v[164:165] op_sel_hi:[1,0]
	v_pk_mul_f32 v[20:21], v[20:21], v[164:165] op_sel_hi:[1,0]
	v_pk_mul_f32 v[18:19], v[18:19], v[164:165] op_sel_hi:[1,0]
	v_pk_mul_f32 v[16:17], v[16:17], v[164:165] op_sel_hi:[1,0]
	v_sub_f32_e32 v47, v47, v162
	v_sub_f32_e32 v46, v46, v162
	v_sub_f32_e32 v45, v45, v162
	v_sub_f32_e32 v44, v44, v162
	v_sub_f32_e32 v43, v43, v162
	v_sub_f32_e32 v42, v42, v162
	v_sub_f32_e32 v41, v41, v162
	v_sub_f32_e32 v40, v40, v162
	v_sub_f32_e32 v39, v39, v162
	v_sub_f32_e32 v38, v38, v162
	v_sub_f32_e32 v37, v37, v162
	v_sub_f32_e32 v36, v36, v162
	v_sub_f32_e32 v35, v35, v162
	v_sub_f32_e32 v34, v34, v162
	v_sub_f32_e32 v33, v33, v162
	v_sub_f32_e32 v32, v32, v162
	s_branch .LBB0_109
